# phase-1 acquire also invalidates L1 (issued before the poll) before normmod1 reads MOD with plain loads
# speedup vs baseline: 1.0028x; 1.0028x over previous
.Lpf_t3:
	v_lshl_add_u32 v4, v194, 2, vcc_hi
	v_and_b32_e32 v2, vcc_lo, v194
	v_cmp_eq_u32_e32 vcc, s1, v2
	v_mov_b32_e32 v3, s100
	v_cndmask_b32_e32 v3, 0, v3, vcc
	v_cmp_gt_u32_e32 vcc, 32, v194
	v_cndmask_b32_e32 v3, 0, v3, vcc
	v_readlane_b32 s0, v253, 5
	v_readlane_b32 s1, v253, 6
	s_movk_i32 s100, 0x1000
	s_nop 4
	s_cmp_eq_u32 s46, 1
	s_cbranch_scc0 .Lpf_poll
	buffer_inv sc1
